# v35 + mLSTM item-start gate scan via DPP scans and hw log (same scheme as the in-loop scan)
# speedup vs baseline: 1.0058x; 1.0012x over previous
; #define GLOAD(c) do { const float* g0 = gates + MTOK((c) * 128 + 2 * lane) * 16; const float* g1 = gates + MTOK((c) * 128 + 2 * lane + 1) * 16; \
;                 gi0 = g0[gcol]; gf0 = g0[gcol + 4]; gi1 = g1[gcol]; gf1 = g1[gcol + 4]; } while (0)
; DI float logsig(float x) { return fminf(x, 0.f) - log1pf(__expf(-fabsf(x))); }
; DI void mlstm_phase(LAS unsigned char* lds, const bf16_t* proj, const float* gates, bf16_t* Hfw, bf16_t* Hbw, int G, int bid) {
;     ...
;         MLOAD(0);
;         if (wid == 2) { GLOAD(0); GATES(0); }
.LBB0_828:
	s_or_b64 exec, exec, s[38:39]
	s_bfe_u32 s36, s48, 0x30005
	s_lshl_b32 s38, s36, 13
	s_lshl_b32 s36, s36, 12
	s_and_b32 s50, s48, 1
	s_bfe_u32 s47, s48, 0x20001
	s_bitset1_b32 s36, 16
	s_cmpk_lt_i32 s48, 0x100
	s_movk_i32 s39, 0x2000
	s_cselect_b32 s46, s39, 0x1000
	s_cselect_b32 s96, s38, s36
	s_cmp_eq_u32 s50, 0
	v_not_b32_e32 v0, v155
	v_add_u32_e32 v0, s46, v0
	s_cselect_b64 s[90:91], -1, 0
	s_mov_b32 s98, 0xfffd0000
	s_mov_b32 s100, 0xfffa0000
	s_cselect_b32 s98, 0x30000, s98
	s_cselect_b32 s99, 0, -1
	s_cselect_b32 s100, 0x60000, s100
	s_cselect_b32 s101, 0, -1
	v_readlane_b32 s38, v255, 20
	v_cndmask_b32_e64 v0, v0, v155, s[90:91]
	v_readlane_b32 s39, v255, 21
	v_add_u32_e32 v0, s96, v0
	v_writelane_b32 v255, s48, 22
	v_mov_b64_e32 v[2:3], s[38:39]
	s_waitcnt vmcnt(11)
	v_mad_i64_i32 v[4:5], s[38:39], v0, s33, v[2:3]
	v_not_b32_e32 v0, v156
	v_add_u32_e32 v0, s46, v0
	v_cndmask_b32_e64 v0, v0, v156, s[90:91]
	v_add_u32_e32 v0, s96, v0
	s_waitcnt vmcnt(9)
	v_mad_i64_i32 v[12:13], s[38:39], v0, s33, v[2:3]
	v_not_b32_e32 v0, v157
	v_add_u32_e32 v0, s46, v0
	v_cndmask_b32_e64 v0, v0, v157, s[90:91]
	v_add_u32_e32 v0, s96, v0
	s_waitcnt vmcnt(7)
	v_mad_i64_i32 v[20:21], s[38:39], v0, s33, v[2:3]
	v_not_b32_e32 v0, v158
	v_add_u32_e32 v0, s46, v0
	v_cndmask_b32_e64 v0, v0, v158, s[90:91]
	v_add_u32_e32 v0, s96, v0
	s_waitcnt vmcnt(5)
	v_mad_i64_i32 v[28:29], s[38:39], v0, s33, v[2:3]
	v_not_b32_e32 v0, v159
	v_add_u32_e32 v0, s46, v0
	v_cndmask_b32_e64 v0, v0, v159, s[90:91]
	s_lshl_b32 s38, s48, 3
	v_add_u32_e32 v0, s96, v0
	s_and_b32 s48, s38, 0xc0
	s_waitcnt vmcnt(3)
	v_mad_i64_i32 v[36:37], s[38:39], v0, s33, v[2:3]
	v_not_b32_e32 v0, v160
	v_add_u32_e32 v0, s46, v0
	v_cndmask_b32_e64 v0, v0, v160, s[90:91]
	s_lshl_b32 s40, s47, 9
	s_mov_b32 s41, s37
	v_add_u32_e32 v0, s96, v0
	s_lshl_b32 s36, s47, 8
	v_lshl_add_u64 v[36:37], v[36:37], 0, s[40:41]
	s_lshl_b32 s38, s48, 1
	s_mov_b32 s39, s37
	v_mad_i64_i32 v[2:3], s[48:49], v0, s33, v[2:3]
	v_lshl_add_u64 v[4:5], v[4:5], 0, s[36:37]
	v_mov_b32_e32 v123, v1
	v_lshl_add_u64 v[12:13], v[12:13], 0, s[36:37]
	v_lshl_add_u64 v[20:21], v[20:21], 0, s[36:37]
	v_lshl_add_u64 v[28:29], v[28:29], 0, s[36:37]
	v_lshl_add_u64 v[36:37], v[36:37], 0, s[38:39]
	v_mov_b32_e32 v125, v1
	v_lshl_add_u64 v[2:3], v[2:3], 0, s[40:41]
	v_lshl_add_u64 v[8:9], v[4:5], 0, v[122:123]
	v_lshl_add_u64 v[16:17], v[12:13], 0, v[122:123]
	v_lshl_add_u64 v[24:25], v[20:21], 0, v[122:123]
	v_lshl_add_u64 v[32:33], v[28:29], 0, v[122:123]
	v_lshl_add_u64 v[36:37], v[36:37], 0, v[124:125]
	v_lshl_add_u64 v[2:3], v[2:3], 0, s[38:39]
	global_load_dwordx4 v[4:7], v[8:9], off
	s_nop 0
	global_load_dwordx4 v[8:11], v[8:9], off offset:1024
	s_nop 0
	global_load_dwordx4 v[12:15], v[16:17], off
	s_nop 0
	global_load_dwordx4 v[16:19], v[16:17], off offset:1024
	s_nop 0
	global_load_dwordx4 v[20:23], v[24:25], off
	s_nop 0
	global_load_dwordx4 v[24:27], v[24:25], off offset:1024
	s_nop 0
	global_load_dwordx4 v[28:31], v[32:33], off
	s_nop 0
	global_load_dwordx4 v[32:35], v[32:33], off offset:1024
	v_lshl_add_u64 v[2:3], v[2:3], 0, v[124:125]
	global_load_dwordx4 v[36:39], v[36:37], off offset:2048
	s_nop 0
	global_load_dwordx4 v[40:43], v[2:3], off offset:2048
	s_lshl_b32 s39, s50, 3
	s_or_b32 s39, s39, s47
	s_and_b64 vcc, exec, s[0:1]
	s_cbranch_vccz .LBB0_832
	v_not_b32_e32 v0, v144
	v_add_u32_e32 v0, s46, v0
	v_cndmask_b32_e64 v0, v0, v144, s[90:91]
	v_add_u32_e32 v0, s96, v0
	v_lshlrev_b64 v[2:3], 6, v[0:1]
	v_readlane_b32 s48, v255, 26
	v_sub_u32_e32 v0, s46, v144
	v_readlane_b32 s49, v255, 27
	v_add_u32_e32 v0, -2, v0
	v_or_b32_e32 v44, 1, v144
	v_lshl_add_u64 v[2:3], s[48:49], 0, v[2:3]
	v_cndmask_b32_e64 v0, v0, v44, s[90:91]
	s_lshl_b32 s40, s39, 2
	s_mov_b32 s41, s37
	v_add_u32_e32 v0, s96, v0
	v_lshl_add_u64 v[2:3], v[2:3], 0, s[40:41]
	global_load_dword v123, v[2:3], off offset:16
	v_lshlrev_b64 v[44:45], 6, v[0:1]
	v_lshl_add_u64 v[44:45], s[48:49], 0, v[44:45]
	v_lshl_add_u64 v[44:45], v[44:45], 0, s[40:41]
	global_load_dword v207, v[44:45], off offset:16
	global_load_dword v133, v[44:45], off
	global_load_dword v132, v[2:3], off
	s_waitcnt vmcnt(0)
	v_mov_b32_e32 v134, 0
	v_mul_f32_e64 v44, |v123|, s35
	v_mul_f32_e64 v45, |v207|, s35
	v_exp_f32_e32 v44, v44
	v_exp_f32_e32 v45, v45
	v_min_f32_e32 v2, 0, v123
	v_min_f32_e32 v3, 0, v207
	s_nop 0
	v_add_f32_e32 v46, 1.0, v44
	v_add_f32_e32 v47, 1.0, v45
	v_mul_f32_e32 v48, -0.5, v44
	v_mul_f32_e32 v49, -0.5, v45
	v_log_f32_e32 v46, v46
	v_log_f32_e32 v47, v47
	v_fma_f32 v48, v48, v44, v44
	v_fma_f32 v49, v49, v45, v45
	v_cmp_gt_f32_e32 vcc, 0x39800000, v44
	v_mul_f32_e32 v46, s34, v46
	v_mul_f32_e32 v47, s34, v47
	v_cndmask_b32_e32 v46, v46, v48, vcc
	v_cmp_gt_f32_e32 vcc, 0x39800000, v45
	v_sub_f32_e32 v2, v2, v46
	s_nop 0
	v_cndmask_b32_e32 v47, v47, v49, vcc
	v_sub_f32_e32 v3, v3, v47
	v_add_f32_e32 v44, v2, v3
	v_mov_b32_e32 v45, v44
	s_nop 1
	v_add_f32_dpp v45, v45, v45 row_shr:1 row_mask:0xf bank_mask:0xf
	s_nop 1
	v_add_f32_dpp v45, v45, v45 row_shr:2 row_mask:0xf bank_mask:0xf
	s_nop 1
	v_add_f32_dpp v45, v45, v45 row_shr:4 row_mask:0xf bank_mask:0xf
	s_nop 1
	v_add_f32_dpp v45, v45, v45 row_shr:8 row_mask:0xf bank_mask:0xf
	s_nop 1
	v_add_f32_dpp v45, v45, v45 row_bcast:15 row_mask:0xa bank_mask:0xf
	s_nop 1
	v_add_f32_dpp v45, v45, v45 row_bcast:31 row_mask:0xc bank_mask:0xf
	s_nop 0
	v_sub_f32_e32 v46, v45, v44
	v_add_f32_e32 v44, v2, v46
	v_sub_f32_e32 v3, v133, v45
	v_sub_f32_e32 v2, v132, v44
	v_mov_b32_e32 v47, v204
	v_max_f32_e32 v46, v2, v3
	s_nop 1
	v_max_f32_dpp v46, v46, v46 row_shr:1 row_mask:0xf bank_mask:0xf
	s_nop 1
	v_max_f32_dpp v46, v46, v46 row_shr:2 row_mask:0xf bank_mask:0xf
	s_nop 1
	v_max_f32_dpp v46, v46, v46 row_shr:4 row_mask:0xf bank_mask:0xf
	s_nop 1
	v_max_f32_dpp v46, v46, v46 row_shr:8 row_mask:0xf bank_mask:0xf
	s_nop 1
	v_max_f32_dpp v46, v46, v46 row_bcast:15 row_mask:0xa bank_mask:0xf
	s_nop 1
	v_max_f32_dpp v46, v46, v46 row_bcast:31 row_mask:0xc bank_mask:0xf
	s_nop 1
	v_mov_b32_dpp v47, v46 wave_shr:1 row_mask:0xf bank_mask:0xf
	v_max_f32_e32 v49, v134, v46
	v_max3_f32 v48, v134, v47, v2
	s_nop 0
	v_readlane_b32 s40, v49, 63
	v_readlane_b32 s41, v45, 63
	ds_write_b64 v145, v[2:3]
	ds_write_b64 v189, v[48:49]
	ds_write_b64 v187, v[44:45]
	v_readlane_b32 s48, v255, 39
	v_mov_b32_e32 v135, s40
	s_nop 3
	v_mov_b32_e32 v50, s48
	s_and_saveexec_b64 vcc, s[8:9]
	s_nop 0
	ds_write_b64 v50, v[134:135]
	s_mov_b64 exec, vcc
	s_nop 1
	v_add_f32_e32 v134, s41, v135
	s_or_b32 s40, s39, 4
	s_mov_b32 s41, s37
	v_mov_b32_e32 v84, v253
	s_branch .LBB0_834
